# v30 plus strategy 7.4: one static s_setprio 1 for waves 4-7 at the entry of the attention work-queue phase (GEMM loops reset it afterwards)
# speedup vs baseline: 1.0021x; 1.0021x over previous
.LBB0_776:
	s_cmp_lt_i32 s74, 6
	v_writelane_b32 v254, s72, 40
	s_cselect_b64 s[4:5], -1, 0
	s_and_b64 s[0:1], s[4:5], s[2:3]
	v_writelane_b32 v254, s73, 41
	v_writelane_b32 v254, s74, 42
	v_writelane_b32 v254, s75, 43
	v_writelane_b32 v254, s76, 44
	s_andn2_b64 vcc, exec, s[0:1]
	s_nop 0
	v_writelane_b32 v254, s77, 45
	s_cbranch_vccnz .LBB0_2355
	s_add_u32 s36, s72, 0xe000000
	s_addc_u32 s37, s73, 0
	v_writelane_b32 v254, s4, 46
	s_add_u32 s0, s72, 0x300000
	s_addc_u32 s1, s73, 0
	v_writelane_b32 v254, s5, 47
	v_writelane_b32 v254, s0, 48
	s_mov_b32 s71, 0
	s_mov_b32 s79, s71
	v_writelane_b32 v254, s1, 49
	s_add_u32 s0, s72, 0x700000
	s_addc_u32 s1, s73, 0
	v_writelane_b32 v254, s0, 50
	s_mov_b64 s[86:87], s[74:75]
	s_mov_b64 s[84:85], s[72:73]
	v_writelane_b32 v254, s1, 51
	s_add_u32 s0, s72, 0x6000000
	s_addc_u32 s1, s73, 0
	v_writelane_b32 v254, s0, 52
	s_mov_b32 s2, s78
	v_and_b32_e32 v214, 0x3ff, v0
	v_writelane_b32 v254, s1, 53
	s_lshl_b64 s[0:1], s[78:79], 20
	s_add_u32 s0, s72, s0
	s_addc_u32 s1, s73, s1
	s_add_u32 s86, s0, 0x2c000000
	s_addc_u32 s87, s1, 0
	s_add_u32 s0, s76, 0xb0
	s_addc_u32 s1, s77, 0
	v_writelane_b32 v254, s0, 54
	v_cmp_eq_u32_e64 s[10:11], 0, v214
	v_mov_b32_e32 v149, 0
	v_writelane_b32 v254, s1, 55
	s_add_u32 s0, s84, 0x900000
	v_writelane_b32 v254, s0, 56
	s_addc_u32 s0, s85, 0
	v_writelane_b32 v254, s0, 57
	s_mov_b32 s0, 0x20000
	s_addk_i32 s0, 0x100
	v_writelane_b32 v254, s0, 58
	v_mov_b32_e32 v1, s0
	s_mov_b32 s0, 0x16000
	s_addk_i32 s0, 0x100
	v_writelane_b32 v254, s0, 60
	s_mov_b32 s0, s2
	v_writelane_b32 v254, s0, 61
	v_mbcnt_lo_u32_b32 v2, -1, 0
	s_movk_i32 s38, 0x100
	v_writelane_b32 v254, s1, 62
	v_writelane_b32 v254, s36, 63
	s_movk_i32 s33, 0x1e00
	s_brev_b32 s75, 1
	v_writelane_b32 v255, s37, 0
	v_writelane_b32 v255, s10, 1
	s_mov_b32 s39, 0xff800000
	s_mov_b64 s[90:91], 0x900
	s_mov_b64 s[92:93], 0x940
	s_mov_b64 s[94:95], 0xb80
	s_mov_b64 s[96:97], 0x1200
	s_mov_b64 s[68:69], 0x1240
	s_mov_b64 s[78:79], 0x1b00
	s_mov_b64 s[54:55], 0x1b40
	v_mov_b32_e32 v147, 0x1e00
	v_bfrev_b32_e32 v172, 1
	v_mov_b32_e32 v173, 0xfa
	v_mov_b32_e32 v216, 0xff800000
	v_mbcnt_hi_u32_b32 v217, -1, v2
	v_mov_b32_e32 v215, 0x200
	v_mov_b32_e32 v229, 0x100
	s_mov_b32 s0, s2
	s_mov_b32 s2, 0
	v_writelane_b32 v255, s11, 2
	v_readfirstlane_b32 s98, v0
	s_nop 3
	s_and_b32 s98, s98, 0x3ff
	s_lshr_b32 s98, s98, 6
	s_cmp_ge_u32 s98, 4
	s_cbranch_scc0 .Lprio_done_a
	s_setprio 1
.Lprio_done_a:
	s_branch .LBB0_779
.LBB0_778:
	v_readlane_b32 s2, v255, 4
	v_readlane_b32 s0, v255, 3
	s_add_i32 s2, s2, 1
	s_add_i32 s0, s0, 1
	s_cmp_lg_u32 s2, 8
	s_cbranch_scc0 .LBB0_2354

.LBB0_3035:
	s_cmp_lt_i32 s74, 14
	s_cselect_b64 s[4:5], -1, 0
	s_and_b64 s[0:1], s[4:5], s[2:3]
	s_andn2_b64 vcc, exec, s[0:1]
	s_cbranch_vccnz .LBB0_4614
	s_add_u32 s2, s72, 0xe000000
	s_addc_u32 s3, s73, 0
	v_writelane_b32 v254, s4, 46
	s_add_u32 s0, s72, 0x300000
	s_addc_u32 s1, s73, 0
	v_writelane_b32 v254, s5, 47
	v_writelane_b32 v254, s0, 48
	s_mov_b32 s37, 0
	s_mov_b32 s79, s37
	v_writelane_b32 v254, s1, 49
	s_add_u32 s0, s72, 0x700000
	s_addc_u32 s1, s73, 0
	v_writelane_b32 v255, s0, 1
	s_mov_b32 s4, s78
	v_and_b32_e32 v214, 0x3ff, v0
	v_writelane_b32 v255, s1, 2
	s_add_u32 s0, s72, 0x6000000
	s_addc_u32 s1, s73, 0
	v_writelane_b32 v255, s0, 25
	v_cmp_eq_u32_e64 s[10:11], 0, v214
	v_mov_b32_e32 v149, 0
	v_writelane_b32 v255, s1, 26
	s_lshl_b64 s[0:1], s[78:79], 20
	s_add_u32 s0, s72, s0
	s_addc_u32 s1, s73, s1
	s_waitcnt lgkmcnt(0)
	s_add_u32 s62, s0, 0x2c000000
	s_addc_u32 s63, s1, 0
	s_add_u32 s0, s76, 0xb0
	s_addc_u32 s1, s77, 0
	v_writelane_b32 v255, s0, 5
	v_mbcnt_lo_u32_b32 v2, -1, 0
	s_movk_i32 s38, 0x100
	v_writelane_b32 v255, s1, 6
	s_add_u32 s0, s72, 0x900000
	v_writelane_b32 v254, s0, 57
	s_addc_u32 s0, s73, 0
	v_writelane_b32 v254, s0, 56
	s_mov_b32 s0, 0x20000
	s_addk_i32 s0, 0x100
	v_writelane_b32 v255, s0, 18
	v_mov_b32_e32 v1, s0
	s_mov_b32 s0, 0x16000
	s_addk_i32 s0, 0x100
	v_writelane_b32 v254, s0, 60
	s_mov_b32 s0, s4
	v_writelane_b32 v254, s0, 61
	v_writelane_b32 v255, s2, 23
	s_movk_i32 s33, 0x1e00
	v_writelane_b32 v254, s1, 62
	v_writelane_b32 v254, s10, 58
	s_brev_b32 s57, 1
	s_mov_b32 s39, 0xff800000
	s_mov_b64 s[70:71], 0x900
	s_mov_b64 s[72:73], 0x940
	s_mov_b64 s[74:75], 0xb80
	s_mov_b64 s[76:77], 0x1200
	s_mov_b64 s[78:79], 0x1240
	s_mov_b64 s[84:85], 0x1b00
	s_mov_b64 s[86:87], 0x1b40
	v_mov_b32_e32 v147, 0x1e00
	v_bfrev_b32_e32 v172, 1
	v_mov_b32_e32 v173, 0xfa
	v_mov_b32_e32 v216, 0xff800000
	v_mbcnt_hi_u32_b32 v217, -1, v2
	v_mov_b32_e32 v215, 0x200
	v_mov_b32_e32 v229, 0x100
	s_mov_b32 s0, s4
	s_mov_b32 s4, 0
	v_writelane_b32 v255, s3, 24
	v_writelane_b32 v254, s11, 59
	v_readfirstlane_b32 s98, v0
	s_nop 3
	s_and_b32 s98, s98, 0x3ff
	s_lshr_b32 s98, s98, 6
	s_cmp_ge_u32 s98, 4
	s_cbranch_scc0 .Lprio_done_b
	s_setprio 1
.Lprio_done_b:
	s_branch .LBB0_3038
.LBB0_3037:
	v_readlane_b32 s4, v255, 4
	v_readlane_b32 s0, v255, 3
	s_add_i32 s4, s4, 1
	s_add_i32 s0, s0, 1
	s_cmp_lg_u32 s4, 8
	s_cbranch_scc0 .LBB0_4613
